# e20: dm_gen's 16-lane second pass rotates over the 8 waves by row (was always wave 0), on top of e18
# speedup vs baseline: 1.0040x; 1.0040x over previous
.LBB0_1334:
	s_bitcmp1_b32 s90, 2
	s_cbranch_scc1 .LBB0_1373
	s_cmpk_gt_i32 s2, 0x20bf
	s_cbranch_scc1 .LBB0_1373
	s_mov_b32 s29, 0
	s_mul_i32 s4, s21, 0x2100
	s_mul_hi_i32 s5, s21, 0x2100
	s_add_u32 s4, s92, s4
	s_waitcnt vmcnt(0)
	v_mov_b32_e32 v2, 0
	v_mov_b32_e32 v3, 0
	s_addc_u32 s5, s93, s5
	s_movk_i32 s0, 0x210
	v_lshl_add_u64 v[2:3], s[4:5], 0, v[2:3]
	s_mov_b64 s[4:5], 0x11200000
	v_lshlrev_b32_e32 v1, 3, v0
	v_cmp_gt_u32_e64 s[0:1], s0, v0
	v_lshl_add_u64 v[2:3], v[2:3], 0, s[4:5]
	v_or_b32_e32 v6, 7, v1
	v_or_b32_e32 v7, 1, v1
	s_add_i32 s22, s2, 0xf40
	v_or_b32_e32 v8, 2, v1
	v_or_b32_e32 v9, 3, v1
	v_or_b32_e32 v10, 4, v1
	v_or_b32_e32 v11, 5, v1
	v_or_b32_e32 v12, 6, v1
	s_movk_i32 s23, 0xfff
	s_movk_i32 s24, 0x201
	s_movk_i32 s25, 0x200
	s_movk_i32 s26, 0x1001
	s_mov_b64 s[6:7], 0x2000
	s_mov_b64 s[8:9], 0x84000
	s_branch .LBB0_1338
.LBB0_1337:
	s_or_b64 exec, exec, s[10:11]
	s_add_i32 s29, s29, 1
	s_add_i32 s4, s21, 64
	s_add_i32 s22, s22, 64
	v_lshl_add_u64 v[2:3], v[2:3], 0, s[8:9]
	s_cmpk_gt_i32 s21, 0x1fbf
	s_mov_b32 s21, s4
	s_cbranch_scc1 .LBB0_1373
.LBB0_1338:
	s_and_saveexec_b64 s[10:11], s[0:1]
	s_cbranch_execz .LBB0_1337
	s_and_b32 s4, s22, 0xfff
	s_lshl_b32 s27, s4, 12
	s_cmpk_gt_u32 s21, 0xfff
	s_cselect_b64 s[16:17], -1, 0
	v_cndmask_b32_e64 v4, 0, 1, s[16:17]
	v_lshl_add_u32 v33, s29, 6, v0
	v_and_b32_e32 v33, 0x1ff, v33
	v_lshlrev_b32_e32 v1, 3, v33
	v_lshlrev_b32_e32 v34, 4, v33
	v_mov_b32_e32 v35, 0
	v_or_b32_e32 v6, 7, v1
	v_or_b32_e32 v7, 1, v1
	v_or_b32_e32 v8, 2, v1
	v_or_b32_e32 v9, 3, v1
	v_or_b32_e32 v10, 4, v1
	v_or_b32_e32 v11, 5, v1
	v_or_b32_e32 v12, 6, v1
	v_mul_u32_u24_e32 v13, s4, v7
	v_mul_u32_u24_e32 v14, s4, v8
	v_mul_u32_u24_e32 v15, s4, v9
	v_mul_u32_u24_e32 v16, s4, v10
	v_mul_u32_u24_e32 v17, s4, v11
	v_mul_u32_u24_e32 v18, s4, v12
	v_mul_u32_u24_e32 v19, s4, v6
	v_mul_u32_u24_e32 v20, s4, v1
	s_mov_b32 s28, 0
	s_mov_b64 s[12:13], 0
	v_cmp_ne_u32_e64 s[4:5], 1, v4
	v_mov_b32_e32 v21, v6
	v_lshl_add_u64 v[4:5], v[2:3], 0, v[34:35]
	v_mov_b32_e32 v22, v33
	s_branch .LBB0_1341
